# v40 plus: proj_a/proj_b grid barrier removed; unit-closing barrier in diff-attn no longer waits for the O stores
# speedup vs baseline: 1.0021x; 1.0021x over previous
; #define LAS __attribute__((address_space(3)))
; __device__ __forceinline__ unsigned pk2(float lo, float hi) { f32x2 v = {lo, hi}; bf16x2_t b = __builtin_convertvector(v, bf16x2_t); return __builtin_bit_cast(unsigned, b); }
; __device__ __forceinline__ void attn_b_unit(LAS unsigned char* lds, const bf16_t* __restrict__ Q, const bf16_t* __restrict__ K, const bf16_t* __restrict__ V, bf16_t* __restrict__ O, int q0) {
;     ...
;     const float ltot = lrun + ((const LAS float*)(lds + LOFF + (rg * 2 + (g ^ 1)) * 128))[r32];
;     LAS float* wsf = (LAS float*)(lds + WOFF + wid * 128);
;     if (hi == 0) wsf[r32] = 1.0f / ltot;
;     asm volatile("s_waitcnt lgkmcnt(0)" ::: "memory");
;     f32x4 fv[4];
; #pragma unroll
;     for (int gq = 0; gq < 4; ++gq) fv[gq] = *(const LAS f32x4*)(wsf + 8 * gq + 4 * hi);
;     asm volatile("" ::: "memory");
;     LAS bf16_t* stg = (LAS bf16_t*)(lds + POFF + wid * 4096);
; #pragma unroll
;     for (int hf = 0; hf < 2; ++hf) {
; #pragma unroll
;         for (int d2 = 0; d2 < 2; ++d2)
; #pragma unroll
;             for (int r = 0; r < 16; ++r) { const int orow = (r & 3) + 8 * (r >> 2) + 4 * hi;
;                 const float v = o[2 * hf + d2][r] * fv[r >> 2][r & 3];
;                 stg[orow * 64 + d2 * 32 + r32] = (bf16_t)(pk2(v, 0.f) & 0xffffu); }
;         asm volatile("s_waitcnt lgkmcnt(0)" ::: "memory");
; #pragma unroll
;         for (int i = 0; i < 4; ++i) { const int row = i * 8 + (lane >> 3), ch = lane & 7;
;             const u32x4 v = *(const LAS u32x4*)(stg + row * 64 + ch * 8);
;             *(u32x4*)(O + (size_t)(qw + row) * 4096 + g * 128 + hf * 64 + ch * 8) = v; }
.LBB0_251:
	s_or_b64 exec, exec, s[36:37]
	s_lshl_b32 s14, s95, 12
	s_add_u32 s14, s41, s14
	s_waitcnt lgkmcnt(0)
	s_addc_u32 s15, s44, 0
	ds_read_b128 v[68:71], v136
	ds_read_b128 v[72:75], v136 offset:32
	ds_read_b128 v[76:79], v136 offset:64
	ds_read_b128 v[80:83], v136 offset:96
	v_lshlrev_b32_e32 v0, 1, v134
	v_ashrrev_i32_e32 v67, 31, v66
	s_add_i32 s97, s97, 0x18000
	v_and_b32_e32 v0, 0x70, v0
	v_lshl_add_u64 v[66:67], v[66:67], 1, s[14:15]
	v_lshlrev_b32_e32 v84, 1, v133
	v_add_u32_e32 v86, s97, v0
	v_lshl_add_u64 v[66:67], v[66:67], 0, v[0:1]
	s_waitcnt lgkmcnt(0)
	v_mul_f32_e32 v0, v50, v68
	v_lshlrev_b32_e32 v50, 9, v115
	v_cvt_pk_bf16_f32 v0, v0, s0
	v_add3_u32 v50, s97, v84, v50
	ds_write_b16 v50, v0
	v_mul_f32_e32 v0, v51, v69
	v_cvt_pk_bf16_f32 v0, v0, s0
	ds_write_b16 v50, v0 offset:128
	v_mul_f32_e32 v0, v52, v70
	v_cvt_pk_bf16_f32 v0, v0, s0
	ds_write_b16 v50, v0 offset:256
	v_mul_f32_e32 v0, v53, v71
	v_cvt_pk_bf16_f32 v0, v0, s0
	ds_write_b16 v50, v0 offset:384
	v_mul_f32_e32 v0, v54, v72
	v_cvt_pk_bf16_f32 v0, v0, s0
	ds_write_b16 v50, v0 offset:1024
	v_mul_f32_e32 v0, v55, v73
	v_cvt_pk_bf16_f32 v0, v0, s0
	ds_write_b16 v50, v0 offset:1152
	v_mul_f32_e32 v0, v56, v74
	v_cvt_pk_bf16_f32 v0, v0, s0
	ds_write_b16 v50, v0 offset:1280
	v_mul_f32_e32 v0, v57, v75
	v_cvt_pk_bf16_f32 v0, v0, s0
	ds_write_b16 v50, v0 offset:1408
	v_mul_f32_e32 v0, v58, v76
	v_cvt_pk_bf16_f32 v0, v0, s0
	ds_write_b16 v50, v0 offset:2048
	v_mul_f32_e32 v0, v59, v77
	v_cvt_pk_bf16_f32 v0, v0, s0
	ds_write_b16 v50, v0 offset:2176
	v_mul_f32_e32 v0, v60, v78
	v_cvt_pk_bf16_f32 v0, v0, s0
	ds_write_b16 v50, v0 offset:2304
	v_mul_f32_e32 v0, v61, v79
	v_cvt_pk_bf16_f32 v0, v0, s0
	ds_write_b16 v50, v0 offset:2432
	v_mul_f32_e32 v0, v62, v80
	v_cvt_pk_bf16_f32 v0, v0, s0
	ds_write_b16 v50, v0 offset:3072
	v_mul_f32_e32 v0, v63, v81
	v_cvt_pk_bf16_f32 v0, v0, s0
	ds_write_b16 v50, v0 offset:3200
	v_mul_f32_e32 v0, v64, v82
	v_cvt_pk_bf16_f32 v0, v0, s0
	ds_write_b16 v50, v0 offset:3328
	v_mul_f32_e32 v0, v65, v83
	v_cvt_pk_bf16_f32 v0, v0, s0
	ds_write_b16 v50, v0 offset:3456
	v_mul_f32_e32 v0, v34, v68
	v_cvt_pk_bf16_f32 v0, v0, s0
	ds_write_b16 v50, v0 offset:64
	v_mul_f32_e32 v0, v35, v69
	v_cvt_pk_bf16_f32 v0, v0, s0
	ds_write_b16 v50, v0 offset:192
	v_mul_f32_e32 v0, v36, v70
	v_cvt_pk_bf16_f32 v0, v0, s0
	ds_write_b16 v50, v0 offset:320
	v_mul_f32_e32 v0, v37, v71
	v_cvt_pk_bf16_f32 v0, v0, s0
	ds_write_b16 v50, v0 offset:448
	v_mul_f32_e32 v0, v38, v72
	v_cvt_pk_bf16_f32 v0, v0, s0
	ds_write_b16 v50, v0 offset:1088
	v_mul_f32_e32 v0, v39, v73
	v_cvt_pk_bf16_f32 v0, v0, s0
	ds_write_b16 v50, v0 offset:1216
	v_mul_f32_e32 v0, v40, v74
	v_cvt_pk_bf16_f32 v0, v0, s0
	ds_write_b16 v50, v0 offset:1344
	v_mul_f32_e32 v0, v41, v75
	v_cvt_pk_bf16_f32 v0, v0, s0
	ds_write_b16 v50, v0 offset:1472
	v_mul_f32_e32 v0, v42, v76
	v_cvt_pk_bf16_f32 v0, v0, s0
	ds_write_b16 v50, v0 offset:2112
	v_mul_f32_e32 v0, v43, v77
	v_cvt_pk_bf16_f32 v0, v0, s0
	ds_write_b16 v50, v0 offset:2240
	v_mul_f32_e32 v0, v44, v78
	v_cvt_pk_bf16_f32 v0, v0, s0
	ds_write_b16 v50, v0 offset:2368
	v_mul_f32_e32 v0, v45, v79
	v_cvt_pk_bf16_f32 v0, v0, s0
	ds_write_b16 v50, v0 offset:2496
	v_mul_f32_e32 v0, v46, v80
	v_cvt_pk_bf16_f32 v0, v0, s0
	ds_write_b16 v50, v0 offset:3136
	v_mul_f32_e32 v0, v47, v81
	v_cvt_pk_bf16_f32 v0, v0, s0
	ds_write_b16 v50, v0 offset:3264
	v_mul_f32_e32 v0, v48, v82
	v_cvt_pk_bf16_f32 v0, v0, s0
	ds_write_b16 v50, v0 offset:3392
	v_mul_f32_e32 v0, v49, v83
	v_lshrrev_b32_e32 v85, 3, v135
	v_cvt_pk_bf16_f32 v0, v0, s0
	ds_write_b16 v50, v0 offset:3520
	v_or_b32_e32 v0, s94, v85
	v_lshlrev_b32_e32 v0, 13, v0
	v_lshl_add_u64 v[42:43], v[66:67], 0, v[0:1]
	v_or_b32_e32 v0, 8, v85
	v_lshl_add_u32 v87, v85, 7, v86
	s_waitcnt lgkmcnt(0)
	v_lshl_add_u32 v48, v0, 7, v86
	v_or_b32_e32 v0, s94, v0
	ds_read_b128 v[34:37], v87
	v_lshlrev_b32_e32 v0, 13, v0
	ds_read_b128 v[38:41], v48
	v_lshl_add_u64 v[44:45], v[66:67], 0, v[0:1]
	v_or_b32_e32 v0, 16, v85
	v_lshl_add_u32 v49, v0, 7, v86
	v_or_b32_e32 v0, s94, v0
	v_lshlrev_b32_e32 v0, 13, v0
	v_lshl_add_u64 v[46:47], v[66:67], 0, v[0:1]
	v_or_b32_e32 v0, 24, v85
	s_waitcnt lgkmcnt(0)
; #define LAS __attribute__((address_space(3)))
; #define AB_BAR() asm volatile("s_waitcnt vmcnt(0) lgkmcnt(0)\n\ts_barrier" ::: "memory")
; __device__ __forceinline__ void attn_b_unit(LAS unsigned char* lds, const bf16_t* __restrict__ Q, const bf16_t* __restrict__ K, const bf16_t* __restrict__ V, bf16_t* __restrict__ O, int q0) {
;     ...
;         for (int i = 0; i < 4; ++i) { const int row = i * 8 + (lane >> 3), ch = lane & 7;
;             const u32x4 v = *(const LAS u32x4*)(stg + row * 64 + ch * 8);
;             *(u32x4*)(O + (size_t)(qw + row) * 4096 + g * 128 + hf * 64 + ch * 8) = v; }
;         asm volatile("s_waitcnt lgkmcnt(0)" ::: "memory");
;     }
;     AB_BAR();
	global_store_dwordx4 v[42:43], v[34:37], off
	ds_read_b128 v[34:37], v49
	v_lshl_add_u32 v51, v0, 7, v86
	global_store_dwordx4 v[44:45], v[38:41], off
	ds_read_b128 v[38:41], v51
	v_or_b32_e32 v0, s94, v0
	v_lshlrev_b32_e32 v0, 13, v0
	s_waitcnt lgkmcnt(0)
	global_store_dwordx4 v[46:47], v[34:37], off
	s_add_i32 s33, s33, 1
	s_nop 0
	v_lshl_add_u64 v[34:35], v[66:67], 0, v[0:1]
	v_mul_f32_e32 v0, v18, v68
	global_store_dwordx4 v[34:35], v[38:41], off
	v_cvt_pk_bf16_f32 v0, v0, s0
	s_waitcnt lgkmcnt(0)
	ds_write_b16 v50, v0
	v_mul_f32_e32 v0, v19, v69
	v_cvt_pk_bf16_f32 v0, v0, s0
	ds_write_b16 v50, v0 offset:128
	v_mul_f32_e32 v0, v20, v70
	v_cvt_pk_bf16_f32 v0, v0, s0
	ds_write_b16 v50, v0 offset:256
	v_mul_f32_e32 v0, v21, v71
	v_cvt_pk_bf16_f32 v0, v0, s0
	ds_write_b16 v50, v0 offset:384
	v_mul_f32_e32 v0, v22, v72
	v_cvt_pk_bf16_f32 v0, v0, s0
	ds_write_b16 v50, v0 offset:1024
	v_mul_f32_e32 v0, v23, v73
	v_cvt_pk_bf16_f32 v0, v0, s0
	ds_write_b16 v50, v0 offset:1152
	v_mul_f32_e32 v0, v24, v74
	v_cvt_pk_bf16_f32 v0, v0, s0
	ds_write_b16 v50, v0 offset:1280
	v_mul_f32_e32 v0, v25, v75
	v_cvt_pk_bf16_f32 v0, v0, s0
	ds_write_b16 v50, v0 offset:1408
	v_mul_f32_e32 v0, v26, v76
	v_cvt_pk_bf16_f32 v0, v0, s0
	ds_write_b16 v50, v0 offset:2048
	v_mul_f32_e32 v0, v27, v77
	v_cvt_pk_bf16_f32 v0, v0, s0
	ds_write_b16 v50, v0 offset:2176
	v_mul_f32_e32 v0, v28, v78
	v_cvt_pk_bf16_f32 v0, v0, s0
	ds_write_b16 v50, v0 offset:2304
	v_mul_f32_e32 v0, v29, v79
	v_cvt_pk_bf16_f32 v0, v0, s0
	ds_write_b16 v50, v0 offset:2432
	v_mul_f32_e32 v0, v30, v80
	v_cvt_pk_bf16_f32 v0, v0, s0
	ds_write_b16 v50, v0 offset:3072
	v_mul_f32_e32 v0, v31, v81
	v_cvt_pk_bf16_f32 v0, v0, s0
	ds_write_b16 v50, v0 offset:3200
	v_mul_f32_e32 v0, v32, v82
	v_cvt_pk_bf16_f32 v0, v0, s0
	ds_write_b16 v50, v0 offset:3328
	v_mul_f32_e32 v0, v33, v83
	v_cvt_pk_bf16_f32 v0, v0, s0
	ds_write_b16 v50, v0 offset:3456
	v_mul_f32_e32 v0, v2, v68
	v_cvt_pk_bf16_f32 v0, v0, s0
	ds_write_b16 v50, v0 offset:64
	v_mul_f32_e32 v0, v3, v69
	v_cvt_pk_bf16_f32 v0, v0, s0
	ds_write_b16 v50, v0 offset:192
	v_mul_f32_e32 v0, v4, v70
	v_cvt_pk_bf16_f32 v0, v0, s0
	ds_write_b16 v50, v0 offset:320
	v_mul_f32_e32 v0, v5, v71
	v_cvt_pk_bf16_f32 v0, v0, s0
	ds_write_b16 v50, v0 offset:448
	v_mul_f32_e32 v0, v6, v72
	v_cvt_pk_bf16_f32 v0, v0, s0
	ds_write_b16 v50, v0 offset:1088
	v_mul_f32_e32 v0, v7, v73
	v_cvt_pk_bf16_f32 v0, v0, s0
	ds_write_b16 v50, v0 offset:1216
	v_mul_f32_e32 v0, v8, v74
	v_cvt_pk_bf16_f32 v0, v0, s0
	ds_write_b16 v50, v0 offset:1344
	v_mul_f32_e32 v0, v9, v75
	v_cvt_pk_bf16_f32 v0, v0, s0
	ds_write_b16 v50, v0 offset:1472
	v_mul_f32_e32 v0, v10, v76
	v_cvt_pk_bf16_f32 v0, v0, s0
	ds_write_b16 v50, v0 offset:2112
	v_mul_f32_e32 v0, v11, v77
	v_cvt_pk_bf16_f32 v0, v0, s0
	ds_write_b16 v50, v0 offset:2240
	v_mul_f32_e32 v0, v12, v78
	v_cvt_pk_bf16_f32 v0, v0, s0
	ds_write_b16 v50, v0 offset:2368
	v_mul_f32_e32 v0, v13, v79
	v_cvt_pk_bf16_f32 v0, v0, s0
	ds_write_b16 v50, v0 offset:2496
	v_mul_f32_e32 v0, v14, v80
	v_cvt_pk_bf16_f32 v0, v0, s0
	ds_write_b16 v50, v0 offset:3136
	v_mul_f32_e32 v0, v15, v81
	v_cvt_pk_bf16_f32 v0, v0, s0
	ds_write_b16 v50, v0 offset:3264
	v_mul_f32_e32 v0, v16, v82
	v_cvt_pk_bf16_f32 v0, v0, s0
	ds_write_b16 v50, v0 offset:3392
	v_mul_f32_e32 v0, v17, v83
	v_cvt_pk_bf16_f32 v0, v0, s0
	ds_write_b16 v50, v0 offset:3520
	s_waitcnt lgkmcnt(0)
	ds_read_b128 v[2:5], v87
	ds_read_b128 v[6:9], v48
	ds_read_b128 v[10:13], v49
	ds_read_b128 v[14:17], v51
	s_waitcnt lgkmcnt(0)
	global_store_dwordx4 v[42:43], v[2:5], off offset:128
	global_store_dwordx4 v[44:45], v[6:9], off offset:128
	global_store_dwordx4 v[46:47], v[10:13], off offset:128
	global_store_dwordx4 v[34:35], v[14:17], off offset:128
	s_waitcnt lgkmcnt(0)
	s_waitcnt lgkmcnt(0)
	s_barrier
	s_xor_b64 s[0:1], s[0:1], -1
	s_cmp_eq_u32 s33, 2
	s_cbranch_scc1 .LBB0_284
